# row-max tree 20->8 ops in all attention cores; P2 compress MLP k-loop: 16 independent loads/iter double-buffered
# speedup vs baseline: 1.0985x; 1.0172x over previous
.LBB0_391:
	v_min_u32_e32 v0, 0x7fff, v19
	v_mul_u32_u24_e32 v0, 0xe00, v0
	v_lshlrev_b32_e32 v0, 1, v0
	v_lshl_add_u64 v[58:59], v[20:21], 0, v[0:1]
	v_add_u32_e32 v25, 1, v19
	v_min_u32_e32 v25, 0x7fff, v25
	v_mul_u32_u24_e32 v25, 0xe00, v25
	v_lshlrev_b32_e32 v0, 1, v25
	v_lshl_add_u64 v[60:61], v[20:21], 0, v[0:1]
	global_load_dwordx4 v[76:79], v[22:23], off offset:-128
	global_load_dwordx4 v[108:111], v[58:59], off
	global_load_dwordx4 v[80:83], v[22:23], off offset:-96
	global_load_dwordx4 v[112:115], v[58:59], off offset:32
	global_load_dwordx4 v[84:87], v[22:23], off offset:-64
	global_load_dwordx4 v[116:119], v[58:59], off offset:64
	global_load_dwordx4 v[88:91], v[22:23], off offset:-32
	global_load_dwordx4 v[120:123], v[58:59], off offset:96
	global_load_dwordx4 v[92:95], v[22:23], off
	global_load_dwordx4 v[124:127], v[60:61], off
	global_load_dwordx4 v[96:99], v[22:23], off offset:32
	global_load_dwordx4 v[128:131], v[60:61], off offset:32
	global_load_dwordx4 v[100:103], v[22:23], off offset:64
	global_load_dwordx4 v[132:135], v[60:61], off offset:64
	global_load_dwordx4 v[104:107], v[22:23], off offset:96
	global_load_dwordx4 v[136:139], v[60:61], off offset:96
	v_add_u32_e32 v19, 2, v19
	v_lshl_add_u64 v[22:23], v[22:23], 0, s[88:89]
	s_mov_b32 s37, 7
.Lcmp_loop:
	v_min_u32_e32 v0, 0x7fff, v19
	v_mul_u32_u24_e32 v0, 0xe00, v0
	v_lshlrev_b32_e32 v0, 1, v0
	v_lshl_add_u64 v[58:59], v[20:21], 0, v[0:1]
	v_add_u32_e32 v25, 1, v19
	v_min_u32_e32 v25, 0x7fff, v25
	v_mul_u32_u24_e32 v25, 0xe00, v25
	v_lshlrev_b32_e32 v0, 1, v25
	v_lshl_add_u64 v[60:61], v[20:21], 0, v[0:1]
	global_load_dwordx4 v[140:143], v[22:23], off offset:-128
	global_load_dwordx4 v[172:175], v[58:59], off
	global_load_dwordx4 v[144:147], v[22:23], off offset:-96
	global_load_dwordx4 v[176:179], v[58:59], off offset:32
	global_load_dwordx4 v[148:151], v[22:23], off offset:-64
	global_load_dwordx4 v[180:183], v[58:59], off offset:64
	global_load_dwordx4 v[152:155], v[22:23], off offset:-32
	global_load_dwordx4 v[184:187], v[58:59], off offset:96
	global_load_dwordx4 v[156:159], v[22:23], off
	global_load_dwordx4 v[188:191], v[60:61], off
	global_load_dwordx4 v[160:163], v[22:23], off offset:32
	global_load_dwordx4 v[220:223], v[60:61], off offset:32
	global_load_dwordx4 v[164:167], v[22:23], off offset:64
	global_load_dwordx4 v[224:227], v[60:61], off offset:64
	global_load_dwordx4 v[168:171], v[22:23], off offset:96
	global_load_dwordx4 v[228:231], v[60:61], off offset:96
	v_add_u32_e32 v19, 2, v19
	v_lshl_add_u64 v[22:23], v[22:23], 0, s[88:89]
	s_waitcnt vmcnt(16)
	v_mfma_f32_32x32x16_bf16 v[2:17], v[76:79], v[108:111], v[2:17]
	v_mfma_f32_32x32x16_bf16 v[2:17], v[80:83], v[112:115], v[2:17]
	v_mfma_f32_32x32x16_bf16 v[2:17], v[84:87], v[116:119], v[2:17]
	v_mfma_f32_32x32x16_bf16 v[2:17], v[88:91], v[120:123], v[2:17]
	v_mfma_f32_32x32x16_bf16 v[2:17], v[92:95], v[124:127], v[2:17]
	v_mfma_f32_32x32x16_bf16 v[2:17], v[96:99], v[128:131], v[2:17]
	v_mfma_f32_32x32x16_bf16 v[2:17], v[100:103], v[132:135], v[2:17]
	v_mfma_f32_32x32x16_bf16 v[2:17], v[104:107], v[136:139], v[2:17]
	v_min_u32_e32 v0, 0x7fff, v19
	v_mul_u32_u24_e32 v0, 0xe00, v0
	v_lshlrev_b32_e32 v0, 1, v0
	v_lshl_add_u64 v[58:59], v[20:21], 0, v[0:1]
	v_add_u32_e32 v25, 1, v19
	v_min_u32_e32 v25, 0x7fff, v25
	v_mul_u32_u24_e32 v25, 0xe00, v25
	v_lshlrev_b32_e32 v0, 1, v25
	v_lshl_add_u64 v[60:61], v[20:21], 0, v[0:1]
	global_load_dwordx4 v[76:79], v[22:23], off offset:-128
	global_load_dwordx4 v[108:111], v[58:59], off
	global_load_dwordx4 v[80:83], v[22:23], off offset:-96
	global_load_dwordx4 v[112:115], v[58:59], off offset:32
	global_load_dwordx4 v[84:87], v[22:23], off offset:-64
	global_load_dwordx4 v[116:119], v[58:59], off offset:64
	global_load_dwordx4 v[88:91], v[22:23], off offset:-32
	global_load_dwordx4 v[120:123], v[58:59], off offset:96
	global_load_dwordx4 v[92:95], v[22:23], off
	global_load_dwordx4 v[124:127], v[60:61], off
	global_load_dwordx4 v[96:99], v[22:23], off offset:32
	global_load_dwordx4 v[128:131], v[60:61], off offset:32
	global_load_dwordx4 v[100:103], v[22:23], off offset:64
	global_load_dwordx4 v[132:135], v[60:61], off offset:64
	global_load_dwordx4 v[104:107], v[22:23], off offset:96
	global_load_dwordx4 v[136:139], v[60:61], off offset:96
	v_add_u32_e32 v19, 2, v19
	v_lshl_add_u64 v[22:23], v[22:23], 0, s[88:89]
	s_waitcnt vmcnt(16)
	v_mfma_f32_32x32x16_bf16 v[2:17], v[140:143], v[172:175], v[2:17]
	v_mfma_f32_32x32x16_bf16 v[2:17], v[144:147], v[176:179], v[2:17]
	v_mfma_f32_32x32x16_bf16 v[2:17], v[148:151], v[180:183], v[2:17]
	v_mfma_f32_32x32x16_bf16 v[2:17], v[152:155], v[184:187], v[2:17]
	v_mfma_f32_32x32x16_bf16 v[2:17], v[156:159], v[188:191], v[2:17]
	v_mfma_f32_32x32x16_bf16 v[2:17], v[160:163], v[220:223], v[2:17]
	v_mfma_f32_32x32x16_bf16 v[2:17], v[164:167], v[224:227], v[2:17]
	v_mfma_f32_32x32x16_bf16 v[2:17], v[168:171], v[228:231], v[2:17]
	s_sub_u32 s37, s37, 1
	s_cmp_lg_u32 s37, 0
	s_cbranch_scc1 .Lcmp_loop
	v_min_u32_e32 v0, 0x7fff, v19
	v_mul_u32_u24_e32 v0, 0xe00, v0
	v_lshlrev_b32_e32 v0, 1, v0
	v_lshl_add_u64 v[58:59], v[20:21], 0, v[0:1]
	v_add_u32_e32 v25, 1, v19
	v_min_u32_e32 v25, 0x7fff, v25
	v_mul_u32_u24_e32 v25, 0xe00, v25
	v_lshlrev_b32_e32 v0, 1, v25
	v_lshl_add_u64 v[60:61], v[20:21], 0, v[0:1]
	global_load_dwordx4 v[140:143], v[22:23], off offset:-128
	global_load_dwordx4 v[172:175], v[58:59], off
	global_load_dwordx4 v[144:147], v[22:23], off offset:-96
	global_load_dwordx4 v[176:179], v[58:59], off offset:32
	global_load_dwordx4 v[148:151], v[22:23], off offset:-64
	global_load_dwordx4 v[180:183], v[58:59], off offset:64
	global_load_dwordx4 v[152:155], v[22:23], off offset:-32
	global_load_dwordx4 v[184:187], v[58:59], off offset:96
	global_load_dwordx4 v[156:159], v[22:23], off
	global_load_dwordx4 v[188:191], v[60:61], off
	global_load_dwordx4 v[160:163], v[22:23], off offset:32
	global_load_dwordx4 v[220:223], v[60:61], off offset:32
	global_load_dwordx4 v[164:167], v[22:23], off offset:64
	global_load_dwordx4 v[224:227], v[60:61], off offset:64
	global_load_dwordx4 v[168:171], v[22:23], off offset:96
	global_load_dwordx4 v[228:231], v[60:61], off offset:96
	v_add_u32_e32 v19, 2, v19
	v_lshl_add_u64 v[22:23], v[22:23], 0, s[88:89]
	s_waitcnt vmcnt(16)
	v_mfma_f32_32x32x16_bf16 v[2:17], v[76:79], v[108:111], v[2:17]
	v_mfma_f32_32x32x16_bf16 v[2:17], v[80:83], v[112:115], v[2:17]
	v_mfma_f32_32x32x16_bf16 v[2:17], v[84:87], v[116:119], v[2:17]
	v_mfma_f32_32x32x16_bf16 v[2:17], v[88:91], v[120:123], v[2:17]
	v_mfma_f32_32x32x16_bf16 v[2:17], v[92:95], v[124:127], v[2:17]
	v_mfma_f32_32x32x16_bf16 v[2:17], v[96:99], v[128:131], v[2:17]
	v_mfma_f32_32x32x16_bf16 v[2:17], v[100:103], v[132:135], v[2:17]
	v_mfma_f32_32x32x16_bf16 v[2:17], v[104:107], v[136:139], v[2:17]
	s_waitcnt vmcnt(0)
	v_mfma_f32_32x32x16_bf16 v[2:17], v[140:143], v[172:175], v[2:17]
	v_mfma_f32_32x32x16_bf16 v[2:17], v[144:147], v[176:179], v[2:17]
	v_mfma_f32_32x32x16_bf16 v[2:17], v[148:151], v[180:183], v[2:17]
	v_mfma_f32_32x32x16_bf16 v[2:17], v[152:155], v[184:187], v[2:17]
	v_mfma_f32_32x32x16_bf16 v[2:17], v[156:159], v[188:191], v[2:17]
	v_mfma_f32_32x32x16_bf16 v[2:17], v[160:163], v[220:223], v[2:17]
	v_mfma_f32_32x32x16_bf16 v[2:17], v[164:167], v[224:227], v[2:17]
	v_mfma_f32_32x32x16_bf16 v[2:17], v[168:171], v[228:231], v[2:17]
	s_movk_i32 s37, 0x78
	s_add_i32 s36, s36, s30
	s_lshl_b32 s38, s36, 7
	s_ashr_i32 s39, s38, 31
	v_readlane_b32 s44, v252, 34
	s_lshl_b64 s[38:39], s[38:39], 2
	v_readlane_b32 s54, v252, 44
	v_readlane_b32 s55, v252, 45
	s_add_u32 s38, s54, s38
	s_addc_u32 s39, s55, s39
	v_ashrrev_i32_e32 v67, 31, v66
	v_lshl_add_u64 v[20:21], v[66:67], 2, s[38:39]
	v_mov_b32_e32 v19, v1
	v_lshl_add_u64 v[18:19], v[20:21], 0, v[18:19]
	v_lshlrev_b32_e32 v0, 11, v75
	v_lshlrev_b32_e32 v20, 4, v74
	v_add3_u32 v0, 0, v0, v20
	global_load_dwordx4 v[20:23], v[18:19], off
	v_mov_b32_e32 v27, v4
	v_mov_b32_e32 v4, v3
	v_mov_b32_e32 v26, v2
	v_readlane_b32 s45, v252, 35
	v_readlane_b32 s46, v252, 36
	v_readlane_b32 s47, v252, 37
	v_readlane_b32 s48, v252, 38
	v_readlane_b32 s49, v252, 39
	v_readlane_b32 s50, v252, 40
	v_readlane_b32 s51, v252, 41
	v_readlane_b32 s52, v252, 42
	v_readlane_b32 s53, v252, 43
	v_readlane_b32 s56, v252, 46
	v_readlane_b32 s57, v252, 47
	v_readlane_b32 s58, v252, 48
	v_readlane_b32 s59, v252, 49
	s_waitcnt vmcnt(0)
	v_mov_b32_e32 v29, v22
	v_mov_b32_e32 v22, v21
	v_mov_b32_e32 v28, v20
	v_pk_add_f32 v[4:5], v[4:5], v[22:23]
	v_pk_add_f32 v[26:27], v[26:27], v[28:29]
	v_mul_f32_e32 v3, 0xbfb8aa3b, v4
	v_mul_f32_e32 v2, 0xbfb8aa3b, v26
	v_exp_f32_e32 v20, v3
	v_mul_f32_e32 v3, 0xbfb8aa3b, v27
	v_exp_f32_e32 v2, v2
	v_exp_f32_e32 v3, v3
	s_nop 0
	v_pk_add_f32 v[2:3], v[2:3], 1.0 op_sel_hi:[1,0]
	s_nop 0
	v_div_scale_f32 v21, s[38:39], v3, v3, v27
	v_rcp_f32_e32 v22, v21
	s_nop 0
	v_fma_f32 v23, -v21, v22, 1.0
	v_fmac_f32_e32 v22, v23, v22
	v_div_scale_f32 v23, vcc, v27, v3, v27
	v_mul_f32_e32 v25, v23, v22
	v_fma_f32 v28, -v21, v25, v23
	v_fmac_f32_e32 v25, v28, v22
	v_fma_f32 v21, -v21, v25, v23
	v_div_fmas_f32 v21, v21, v22, v25
	v_div_fixup_f32 v22, v21, v3, v27
	v_div_scale_f32 v3, s[38:39], v2, v2, v26
	v_rcp_f32_e32 v21, v3
	s_nop 0
	v_fma_f32 v23, -v3, v21, 1.0
	v_fmac_f32_e32 v21, v23, v21
	v_div_scale_f32 v23, vcc, v26, v2, v26
	v_mul_f32_e32 v25, v23, v21
	v_fma_f32 v27, -v3, v25, v23
	v_fmac_f32_e32 v25, v27, v21
	v_fma_f32 v3, -v3, v25, v23
	v_div_fmas_f32 v3, v3, v21, v25
	v_div_fixup_f32 v23, v3, v2, v26
	v_mul_f32_e32 v2, 0xbfb8aa3b, v5
	v_exp_f32_e32 v21, v2
	s_nop 0
	v_pk_add_f32 v[2:3], v[20:21], 1.0 op_sel_hi:[1,0]
	s_nop 0
	v_div_scale_f32 v20, s[38:39], v3, v3, v5
	v_rcp_f32_e32 v21, v20
	s_nop 0
	v_fma_f32 v25, -v20, v21, 1.0
	v_fmac_f32_e32 v21, v25, v21
	v_div_scale_f32 v25, vcc, v5, v3, v5
	v_mul_f32_e32 v26, v25, v21
	v_fma_f32 v27, -v20, v26, v25
	v_fmac_f32_e32 v26, v27, v21
	v_fma_f32 v20, -v20, v26, v25
	v_div_fmas_f32 v20, v20, v21, v26
	v_div_fixup_f32 v3, v20, v3, v5
	v_div_scale_f32 v5, s[38:39], v2, v2, v4
	v_rcp_f32_e32 v20, v5
	s_nop 0
	v_fma_f32 v21, -v5, v20, 1.0
	v_fmac_f32_e32 v20, v21, v20
	v_div_scale_f32 v21, vcc, v4, v2, v4
	v_mul_f32_e32 v25, v21, v20
	v_fma_f32 v26, -v5, v25, v21
	v_fmac_f32_e32 v25, v26, v20
	v_fma_f32 v5, -v5, v25, v21
	v_div_fmas_f32 v5, v5, v20, v25
	v_div_fixup_f32 v2, v5, v2, v4
	v_cvt_pk_bf16_f32 v4, v23, v22
	global_load_dwordx4 v[20:23], v[18:19], off offset:32
	v_cvt_pk_bf16_f32 v2, v2, v3
	v_and_b32_e32 v3, 0xffff0000, v2
	v_lshlrev_b32_e32 v2, 16, v2
	v_mov_b32_e32 v5, v8
	v_mov_b32_e32 v8, v7
	v_or_b32_sdwa v3, v3, v4 dst_sel:DWORD dst_unused:UNUSED_PAD src0_sel:DWORD src1_sel:WORD_1
	v_or_b32_sdwa v2, v2, v4 dst_sel:DWORD dst_unused:UNUSED_PAD src0_sel:DWORD src1_sel:WORD_0
	v_mov_b32_e32 v4, v6
	s_waitcnt vmcnt(0)
	v_mov_b32_e32 v27, v22
	v_mov_b32_e32 v22, v21
	v_mov_b32_e32 v26, v20
	v_pk_add_f32 v[8:9], v[8:9], v[22:23]
	v_pk_add_f32 v[4:5], v[4:5], v[26:27]
	v_mul_f32_e32 v7, 0xbfb8aa3b, v8
	v_mul_f32_e32 v6, 0xbfb8aa3b, v4
	v_exp_f32_e32 v20, v7
	v_mul_f32_e32 v7, 0xbfb8aa3b, v5
	v_exp_f32_e32 v6, v6
	v_exp_f32_e32 v7, v7
	s_nop 0
	v_pk_add_f32 v[6:7], v[6:7], 1.0 op_sel_hi:[1,0]
	s_nop 0
	v_div_scale_f32 v21, s[38:39], v7, v7, v5
	v_rcp_f32_e32 v22, v21
	s_nop 0
	v_fma_f32 v23, -v21, v22, 1.0
	v_fmac_f32_e32 v22, v23, v22
	v_div_scale_f32 v23, vcc, v5, v7, v5
	v_mul_f32_e32 v25, v23, v22
	v_fma_f32 v26, -v21, v25, v23
	v_fmac_f32_e32 v25, v26, v22
	v_fma_f32 v21, -v21, v25, v23
	v_div_fmas_f32 v21, v21, v22, v25
	v_div_fixup_f32 v7, v21, v7, v5
	v_div_scale_f32 v5, s[38:39], v6, v6, v4
	v_rcp_f32_e32 v21, v5
	s_nop 0
	v_fma_f32 v22, -v5, v21, 1.0
	v_fmac_f32_e32 v21, v22, v21
	v_div_scale_f32 v22, vcc, v4, v6, v4
	v_mul_f32_e32 v23, v22, v21
	v_fma_f32 v25, -v5, v23, v22
	v_fmac_f32_e32 v23, v25, v21
	v_fma_f32 v5, -v5, v23, v22
	v_div_fmas_f32 v5, v5, v21, v23
	v_div_fixup_f32 v6, v5, v6, v4
	v_mul_f32_e32 v4, 0xbfb8aa3b, v9
	v_exp_f32_e32 v21, v4
	v_cvt_pk_bf16_f32 v6, v6, v7
	v_mov_b32_e32 v7, v12
	v_mov_b32_e32 v12, v11
	v_pk_add_f32 v[4:5], v[20:21], 1.0 op_sel_hi:[1,0]
	s_nop 0
	v_div_scale_f32 v20, s[38:39], v5, v5, v9
	v_rcp_f32_e32 v21, v20
	s_nop 0
	v_fma_f32 v22, -v20, v21, 1.0
	v_fmac_f32_e32 v21, v22, v21
	v_div_scale_f32 v22, vcc, v9, v5, v9
	v_mul_f32_e32 v23, v22, v21
	v_fma_f32 v25, -v20, v23, v22
	v_fmac_f32_e32 v23, v25, v21
	v_fma_f32 v20, -v20, v23, v22
	v_div_fmas_f32 v20, v20, v21, v23
	v_div_fixup_f32 v5, v20, v5, v9
	v_div_scale_f32 v9, s[38:39], v4, v4, v8
	v_rcp_f32_e32 v20, v9
	s_nop 0
	v_fma_f32 v21, -v9, v20, 1.0
	v_fmac_f32_e32 v20, v21, v20
	v_div_scale_f32 v21, vcc, v8, v4, v8
	v_mul_f32_e32 v22, v21, v20
	v_fma_f32 v23, -v9, v22, v21
	v_fmac_f32_e32 v22, v23, v20
	v_fma_f32 v9, -v9, v22, v21
	v_div_fmas_f32 v9, v9, v20, v22
	v_div_fixup_f32 v4, v9, v4, v8
	v_cvt_pk_bf16_f32 v4, v4, v5
	v_and_b32_e32 v5, 0xffff0000, v4
	v_lshlrev_b32_e32 v4, 16, v4
	v_or_b32_sdwa v5, v5, v6 dst_sel:DWORD dst_unused:UNUSED_PAD src0_sel:DWORD src1_sel:WORD_1
	v_or_b32_sdwa v4, v4, v6 dst_sel:DWORD dst_unused:UNUSED_PAD src0_sel:DWORD src1_sel:WORD_0
	ds_write_b128 v0, v[2:5]
	global_load_dwordx4 v[2:5], v[18:19], off offset:64
	v_mov_b32_e32 v6, v10
	s_waitcnt vmcnt(0)
	v_mov_b32_e32 v9, v4
	v_mov_b32_e32 v4, v3
	v_mov_b32_e32 v8, v2
	v_pk_add_f32 v[4:5], v[12:13], v[4:5]
	v_pk_add_f32 v[6:7], v[6:7], v[8:9]
	v_mul_f32_e32 v3, 0xbfb8aa3b, v4
	v_mul_f32_e32 v2, 0xbfb8aa3b, v6
	v_exp_f32_e32 v8, v3
	v_mul_f32_e32 v3, 0xbfb8aa3b, v7
	v_exp_f32_e32 v2, v2
	v_exp_f32_e32 v3, v3
	s_nop 0
	v_pk_add_f32 v[2:3], v[2:3], 1.0 op_sel_hi:[1,0]
	s_nop 0
	v_div_scale_f32 v9, s[38:39], v3, v3, v7
	v_rcp_f32_e32 v10, v9
	s_nop 0
	v_fma_f32 v11, -v9, v10, 1.0
	v_fmac_f32_e32 v10, v11, v10
	v_div_scale_f32 v11, vcc, v7, v3, v7
	v_mul_f32_e32 v12, v11, v10
	v_fma_f32 v13, -v9, v12, v11
	v_fmac_f32_e32 v12, v13, v10
	v_fma_f32 v9, -v9, v12, v11
	v_div_fmas_f32 v9, v9, v10, v12
	v_div_fixup_f32 v7, v9, v3, v7
	v_div_scale_f32 v3, s[38:39], v2, v2, v6
	v_rcp_f32_e32 v9, v3
	s_nop 0
	v_fma_f32 v10, -v3, v9, 1.0
	v_fmac_f32_e32 v9, v10, v9
	v_div_scale_f32 v10, vcc, v6, v2, v6
	v_mul_f32_e32 v11, v10, v9
	v_fma_f32 v12, -v3, v11, v10
	v_fmac_f32_e32 v11, v12, v9
	v_fma_f32 v3, -v3, v11, v10
	v_div_fmas_f32 v3, v3, v9, v11
	v_div_fixup_f32 v6, v3, v2, v6
	v_mul_f32_e32 v2, 0xbfb8aa3b, v5
	v_exp_f32_e32 v9, v2
	s_nop 0
	v_pk_add_f32 v[2:3], v[8:9], 1.0 op_sel_hi:[1,0]
	s_nop 0
	v_div_scale_f32 v8, s[38:39], v3, v3, v5
	v_rcp_f32_e32 v9, v8
	s_nop 0
	v_fma_f32 v10, -v8, v9, 1.0
	v_fmac_f32_e32 v9, v10, v9
	v_div_scale_f32 v10, vcc, v5, v3, v5
	v_mul_f32_e32 v11, v10, v9
	v_fma_f32 v12, -v8, v11, v10
	v_fmac_f32_e32 v11, v12, v9
	v_fma_f32 v8, -v8, v11, v10
	v_div_fmas_f32 v8, v8, v9, v11
	v_div_fixup_f32 v3, v8, v3, v5
	v_div_scale_f32 v5, s[38:39], v2, v2, v4
	v_rcp_f32_e32 v8, v5
	s_nop 0
	v_fma_f32 v9, -v5, v8, 1.0
	v_fmac_f32_e32 v8, v9, v8
	v_div_scale_f32 v9, vcc, v4, v2, v4
	v_mul_f32_e32 v10, v9, v8
	v_fma_f32 v11, -v5, v10, v9
	v_fmac_f32_e32 v10, v11, v8
	v_fma_f32 v5, -v5, v10, v9
	v_div_fmas_f32 v5, v5, v8, v10
	v_div_fixup_f32 v2, v5, v2, v4
	v_cvt_pk_bf16_f32 v2, v2, v3
	v_cvt_pk_bf16_f32 v4, v6, v7
	v_and_b32_e32 v3, 0xffff0000, v2
	v_lshlrev_b32_e32 v2, 16, v2
	v_or_b32_sdwa v3, v3, v4 dst_sel:DWORD dst_unused:UNUSED_PAD src0_sel:DWORD src1_sel:WORD_1
	v_or_b32_sdwa v2, v2, v4 dst_sel:DWORD dst_unused:UNUSED_PAD src0_sel:DWORD src1_sel:WORD_0
	global_load_dwordx4 v[4:7], v[18:19], off offset:96
	v_mov_b32_e32 v9, v16
	v_mov_b32_e32 v16, v15
	v_mov_b32_e32 v8, v14
	s_waitcnt vmcnt(0)
	v_mov_b32_e32 v11, v6
	v_mov_b32_e32 v6, v5
	v_mov_b32_e32 v10, v4
	v_pk_add_f32 v[6:7], v[16:17], v[6:7]
	v_pk_add_f32 v[8:9], v[8:9], v[10:11]
	v_mul_f32_e32 v5, 0xbfb8aa3b, v6
	v_mul_f32_e32 v4, 0xbfb8aa3b, v8
	v_exp_f32_e32 v10, v5
	v_mul_f32_e32 v5, 0xbfb8aa3b, v9
	v_exp_f32_e32 v4, v4
	v_exp_f32_e32 v5, v5
	s_nop 0
	v_pk_add_f32 v[4:5], v[4:5], 1.0 op_sel_hi:[1,0]
	s_nop 0
	v_div_scale_f32 v11, s[38:39], v5, v5, v9
	v_rcp_f32_e32 v12, v11
	s_nop 0
	v_fma_f32 v13, -v11, v12, 1.0
	v_fmac_f32_e32 v12, v13, v12
	v_div_scale_f32 v13, vcc, v9, v5, v9
	v_mul_f32_e32 v14, v13, v12
	v_fma_f32 v15, -v11, v14, v13
	v_fmac_f32_e32 v14, v15, v12
	v_fma_f32 v11, -v11, v14, v13
	v_div_fmas_f32 v11, v11, v12, v14
	v_div_fixup_f32 v9, v11, v5, v9
	v_div_scale_f32 v5, s[38:39], v4, v4, v8
	v_rcp_f32_e32 v11, v5
	s_nop 0
	v_fma_f32 v12, -v5, v11, 1.0
	v_fmac_f32_e32 v11, v12, v11
	v_div_scale_f32 v12, vcc, v8, v4, v8
	v_mul_f32_e32 v13, v12, v11
	v_fma_f32 v14, -v5, v13, v12
	v_fmac_f32_e32 v13, v14, v11
	v_fma_f32 v5, -v5, v13, v12
	v_div_fmas_f32 v5, v5, v11, v13
	v_div_fixup_f32 v8, v5, v4, v8
	v_mul_f32_e32 v4, 0xbfb8aa3b, v7
	v_exp_f32_e32 v11, v4
	s_nop 0
	v_pk_add_f32 v[4:5], v[10:11], 1.0 op_sel_hi:[1,0]
	s_nop 0
	v_div_scale_f32 v10, s[38:39], v5, v5, v7
	v_rcp_f32_e32 v11, v10
	s_nop 0
	v_fma_f32 v12, -v10, v11, 1.0
	v_fmac_f32_e32 v11, v12, v11
	v_div_scale_f32 v12, vcc, v7, v5, v7
	v_mul_f32_e32 v13, v12, v11
	v_fma_f32 v14, -v10, v13, v12
	v_fmac_f32_e32 v13, v14, v11
	v_fma_f32 v10, -v10, v13, v12
	v_div_fmas_f32 v10, v10, v11, v13
	v_div_fixup_f32 v5, v10, v5, v7
	v_div_scale_f32 v7, s[38:39], v4, v4, v6
	v_rcp_f32_e32 v10, v7
	s_nop 0
	v_fma_f32 v11, -v7, v10, 1.0
	v_fmac_f32_e32 v10, v11, v10
	v_div_scale_f32 v11, vcc, v6, v4, v6
	v_mul_f32_e32 v12, v11, v10
	v_fma_f32 v13, -v7, v12, v11
	v_fmac_f32_e32 v12, v13, v10
	v_fma_f32 v7, -v7, v12, v11
	v_div_fmas_f32 v7, v7, v10, v12
	v_div_fixup_f32 v4, v7, v4, v6
	v_cvt_pk_bf16_f32 v4, v4, v5
	v_cvt_pk_bf16_f32 v6, v8, v9
	v_and_b32_e32 v5, 0xffff0000, v4
	v_lshlrev_b32_e32 v4, 16, v4
	v_or_b32_sdwa v5, v5, v6 dst_sel:DWORD dst_unused:UNUSED_PAD src0_sel:DWORD src1_sel:WORD_1
	v_or_b32_sdwa v4, v4, v6 dst_sel:DWORD dst_unused:UNUSED_PAD src0_sel:DWORD src1_sel:WORD_0
	v_cmp_gt_i32_e32 vcc, 2, v75
	ds_write_b128 v0, v[2:5] offset:1024
	s_waitcnt lgkmcnt(0)
	s_barrier
	s_and_saveexec_b64 s[38:39], vcc
	s_cbranch_execz .LBB0_315
	v_lshl_add_u32 v2, s36, 6, v66
	v_or_b32_e32 v2, v2, v73
	v_ashrrev_i32_e32 v3, 31, v2
	v_readlane_b32 s44, v252, 34
	v_lshlrev_b32_e32 v0, 2, v24
	v_lshlrev_b64 v[2:3], 8, v[2:3]
	v_readlane_b32 s52, v252, 42
	v_readlane_b32 s53, v252, 43
	v_lshlrev_b32_e32 v0, 1, v0
	v_lshl_add_u32 v76, v74, 4, 0
	v_lshl_add_u64 v[2:3], s[52:53], 0, v[2:3]
	v_lshl_add_u64 v[2:3], v[2:3], 0, v[0:1]
	global_load_dwordx2 v[18:19], v[2:3], off
	global_load_dwordx2 v[20:21], v[2:3], off offset:16
	global_load_dwordx2 v[58:59], v[2:3], off offset:32
	global_load_dwordx2 v[60:61], v[2:3], off offset:48
	global_load_dwordx2 v[54:55], v[2:3], off offset:64
	global_load_dwordx2 v[56:57], v[2:3], off offset:80
	global_load_dwordx2 v[50:51], v[2:3], off offset:96
	global_load_dwordx2 v[52:53], v[2:3], off offset:112
	global_load_dwordx2 v[46:47], v[2:3], off offset:128
	global_load_dwordx2 v[48:49], v[2:3], off offset:144
	global_load_dwordx2 v[42:43], v[2:3], off offset:160
	global_load_dwordx2 v[44:45], v[2:3], off offset:176
	global_load_dwordx2 v[38:39], v[2:3], off offset:192
	global_load_dwordx2 v[40:41], v[2:3], off offset:208
	global_load_dwordx2 v[34:35], v[2:3], off offset:224
	global_load_dwordx2 v[36:37], v[2:3], off offset:240
	ds_read_b128 v[22:25], v76
	s_mov_b64 s[36:37], -1
	s_and_b64 vcc, exec, s[0:1]
	v_readlane_b32 s45, v252, 35
	v_readlane_b32 s46, v252, 36
	v_readlane_b32 s47, v252, 37
	v_readlane_b32 s48, v252, 38
	v_readlane_b32 s49, v252, 39
	v_readlane_b32 s50, v252, 40
	v_readlane_b32 s51, v252, 41
	v_readlane_b32 s54, v252, 44
	v_readlane_b32 s55, v252, 45
	v_readlane_b32 s56, v252, 46
	v_readlane_b32 s57, v252, 47
	v_readlane_b32 s58, v252, 48
	v_readlane_b32 s59, v252, 49
	s_cbranch_vccz .LBB0_395
	s_waitcnt vmcnt(14) lgkmcnt(0)
	v_mfma_f32_32x32x16_bf16 v[2:17], v[22:25], v[18:21], 0
	s_mov_b64 s[36:37], 0

.LBB0_500:
	s_nop 10
	v_max3_f32 v0, v34, v35, v36
	v_max3_f32 v50, v37, v38, v39
	v_max3_f32 v51, v40, v41, v42
	v_max3_f32 v52, v43, v44, v45
	v_max3_f32 v53, v46, v47, v48
	v_max3_f32 v0, v0, v50, v49
	v_max3_f32 v51, v51, v52, v53
	v_max_f32_e32 v0, v0, v51
	v_mov_b32_e32 v50, v0
	s_nop 1
	v_permlane32_swap_b32_e32 v0, v50
	v_max_f32_e32 v0, v0, v50
	v_add_f32_e32 v50, 0x41800000, v173
	v_cmp_gt_f32_e32 vcc, v0, v50
	s_cbranch_vccz .LBB0_502
	s_nop 0
	v_cndmask_b32_e32 v168, v173, v0, vcc
	v_sub_f32_e32 v0, v173, v168
	v_exp_f32_e32 v0, v0
	s_nop 0
	v_mul_f32_e32 v171, v171, v0
	v_pk_mul_f32 v[32:33], v[32:33], v[0:1] op_sel_hi:[1,0]
	v_pk_mul_f32 v[30:31], v[30:31], v[0:1] op_sel_hi:[1,0]
	v_pk_mul_f32 v[28:29], v[28:29], v[0:1] op_sel_hi:[1,0]
	v_pk_mul_f32 v[26:27], v[26:27], v[0:1] op_sel_hi:[1,0]
	v_pk_mul_f32 v[24:25], v[24:25], v[0:1] op_sel_hi:[1,0]
	v_pk_mul_f32 v[22:23], v[22:23], v[0:1] op_sel_hi:[1,0]
	v_pk_mul_f32 v[20:21], v[20:21], v[0:1] op_sel_hi:[1,0]
	v_pk_mul_f32 v[18:19], v[18:19], v[0:1] op_sel_hi:[1,0]
	v_pk_mul_f32 v[16:17], v[16:17], v[0:1] op_sel_hi:[1,0]
	v_pk_mul_f32 v[14:15], v[14:15], v[0:1] op_sel_hi:[1,0]
	v_pk_mul_f32 v[12:13], v[12:13], v[0:1] op_sel_hi:[1,0]
	v_pk_mul_f32 v[10:11], v[10:11], v[0:1] op_sel_hi:[1,0]
	v_pk_mul_f32 v[8:9], v[8:9], v[0:1] op_sel_hi:[1,0]
	v_pk_mul_f32 v[6:7], v[6:7], v[0:1] op_sel_hi:[1,0]
	v_pk_mul_f32 v[4:5], v[4:5], v[0:1] op_sel_hi:[1,0]
	v_pk_mul_f32 v[2:3], v[2:3], v[0:1] op_sel_hi:[1,0]
	s_branch .LBB0_503

.LBB0_510:
	s_nop 10
	v_max3_f32 v0, v66, v67, v68
	v_max3_f32 v2, v69, v70, v71
	v_max3_f32 v3, v72, v73, v74
	v_max3_f32 v4, v75, v76, v77
	v_max3_f32 v5, v78, v79, v80
	v_max3_f32 v0, v0, v2, v81
	v_max3_f32 v3, v3, v4, v5
	v_max_f32_e32 v0, v0, v3
	v_mov_b32_e32 v2, v0
	s_nop 1
	v_permlane32_swap_b32_e32 v0, v2
	v_max_f32_e32 v0, v0, v2
	v_add_f32_e32 v2, 0x41800000, v168
	v_cmp_gt_f32_e32 vcc, v0, v2
	s_cbranch_vccnz .LBB0_491
	v_mov_b64_e32 v[170:171], v[168:169]
	v_mov_b32_e32 v0, v169
	v_mov_b32_e32 v173, v168
	v_mov_b32_e32 v2, v34
	v_mov_b32_e32 v3, v35
	v_mov_b32_e32 v4, v36
	v_mov_b32_e32 v5, v37
	v_mov_b32_e32 v6, v38
	v_mov_b32_e32 v7, v39
	v_mov_b32_e32 v8, v40
	v_mov_b32_e32 v9, v41
	v_mov_b32_e32 v10, v42
	v_mov_b32_e32 v11, v43
	v_mov_b32_e32 v12, v44
	v_mov_b32_e32 v13, v45
	v_mov_b32_e32 v14, v46
	v_mov_b32_e32 v15, v47
	v_mov_b32_e32 v16, v48
	v_mov_b32_e32 v17, v49
	v_mov_b32_e32 v18, v50
	v_mov_b32_e32 v19, v51
	v_mov_b32_e32 v20, v52
	v_mov_b32_e32 v21, v53
	v_mov_b32_e32 v22, v54
	v_mov_b32_e32 v23, v55
	v_mov_b32_e32 v24, v56
	v_mov_b32_e32 v25, v57
	v_mov_b32_e32 v26, v58
	v_mov_b32_e32 v27, v59
	v_mov_b32_e32 v28, v60
	v_mov_b32_e32 v29, v61
	v_mov_b32_e32 v30, v62
	v_mov_b32_e32 v31, v63
	v_mov_b32_e32 v32, v64
	v_mov_b32_e32 v33, v65
	s_branch .LBB0_492

.LBB0_657:
	v_add_u32_e32 v0, 0xfffe7960, v108
	v_cmp_lt_i32_e64 s[38:39], s96, v0
	s_nop 8
	v_max3_f32 v0, v34, v35, v36
	v_max3_f32 v109, v37, v38, v39
	v_max3_f32 v110, v40, v41, v42
	v_max3_f32 v111, v43, v44, v45
	v_max3_f32 v112, v46, v47, v48
	v_max3_f32 v0, v0, v109, v49
	v_max3_f32 v110, v110, v111, v112
	v_max_f32_e32 v0, v0, v110
	v_cndmask_b32_e64 v0, v212, v0, s[38:39]
	v_mov_b32_e32 v109, v0
	s_nop 1
	v_permlane32_swap_b32_e32 v0, v109
	v_max_f32_e32 v0, v0, v109
	v_add_f32_e32 v109, 0x41800000, v75
	v_cmp_gt_f32_e32 vcc, v0, v109
	s_cbranch_vccz .LBB0_654
	s_nop 0
	v_cndmask_b32_e32 v109, v75, v0, vcc
	v_sub_f32_e32 v0, v75, v109
	v_exp_f32_e32 v0, v0
	v_mov_b32_e32 v75, v109
	v_mul_f32_e32 v82, v82, v0
	v_pk_mul_f32 v[16:17], v[16:17], v[0:1] op_sel_hi:[1,0]
	v_pk_mul_f32 v[14:15], v[14:15], v[0:1] op_sel_hi:[1,0]
	v_pk_mul_f32 v[12:13], v[12:13], v[0:1] op_sel_hi:[1,0]
	v_pk_mul_f32 v[10:11], v[10:11], v[0:1] op_sel_hi:[1,0]
	v_pk_mul_f32 v[8:9], v[8:9], v[0:1] op_sel_hi:[1,0]
	v_pk_mul_f32 v[6:7], v[6:7], v[0:1] op_sel_hi:[1,0]
	v_pk_mul_f32 v[4:5], v[4:5], v[0:1] op_sel_hi:[1,0]
	v_pk_mul_f32 v[2:3], v[2:3], v[0:1] op_sel_hi:[1,0]
	v_pk_mul_f32 v[32:33], v[32:33], v[0:1] op_sel_hi:[1,0]
	v_pk_mul_f32 v[30:31], v[30:31], v[0:1] op_sel_hi:[1,0]
	v_pk_mul_f32 v[28:29], v[28:29], v[0:1] op_sel_hi:[1,0]
	v_pk_mul_f32 v[26:27], v[26:27], v[0:1] op_sel_hi:[1,0]
	v_pk_mul_f32 v[24:25], v[24:25], v[0:1] op_sel_hi:[1,0]
	v_pk_mul_f32 v[22:23], v[22:23], v[0:1] op_sel_hi:[1,0]
	v_pk_mul_f32 v[20:21], v[20:21], v[0:1] op_sel_hi:[1,0]
	v_pk_mul_f32 v[18:19], v[18:19], v[0:1] op_sel_hi:[1,0]
	s_branch .LBB0_654

.LBB0_688:
	v_cmp_lt_i32_e64 s[40:41], s96, v0
	s_nop 9
	v_max3_f32 v0, v66, v67, v68
	v_max3_f32 v177, v69, v70, v71
	v_max3_f32 v178, v72, v73, v74
	v_max3_f32 v179, v75, v76, v77
	v_max3_f32 v180, v78, v79, v80
	v_max3_f32 v0, v0, v177, v81
	v_max3_f32 v178, v178, v179, v180
	v_max_f32_e32 v0, v0, v178
	v_cndmask_b32_e64 v0, v212, v0, s[40:41]
	v_mov_b32_e32 v177, v0
	s_nop 1
	v_permlane32_swap_b32_e32 v0, v177
	v_max_f32_e32 v0, v0, v177
	v_add_f32_e32 v177, 0x41800000, v176
	v_cmp_gt_f32_e32 vcc, v0, v177
	s_cbranch_vccz .LBB0_690
	s_nop 0
	v_cndmask_b32_e32 v177, v176, v0, vcc
	v_sub_f32_e32 v0, v176, v177
	v_exp_f32_e32 v0, v0
	v_mov_b32_e32 v176, v177
	v_mul_f32_e32 v161, v161, v0
	v_pk_mul_f32 v[64:65], v[64:65], v[0:1] op_sel_hi:[1,0]
	v_pk_mul_f32 v[62:63], v[62:63], v[0:1] op_sel_hi:[1,0]
	v_pk_mul_f32 v[60:61], v[60:61], v[0:1] op_sel_hi:[1,0]
	v_pk_mul_f32 v[58:59], v[58:59], v[0:1] op_sel_hi:[1,0]
	v_pk_mul_f32 v[56:57], v[56:57], v[0:1] op_sel_hi:[1,0]
	v_pk_mul_f32 v[54:55], v[54:55], v[0:1] op_sel_hi:[1,0]
	v_pk_mul_f32 v[52:53], v[52:53], v[0:1] op_sel_hi:[1,0]
	v_pk_mul_f32 v[50:51], v[50:51], v[0:1] op_sel_hi:[1,0]
	v_pk_mul_f32 v[48:49], v[48:49], v[0:1] op_sel_hi:[1,0]
	v_pk_mul_f32 v[46:47], v[46:47], v[0:1] op_sel_hi:[1,0]
	v_pk_mul_f32 v[44:45], v[44:45], v[0:1] op_sel_hi:[1,0]
	v_pk_mul_f32 v[42:43], v[42:43], v[0:1] op_sel_hi:[1,0]
	v_pk_mul_f32 v[40:41], v[40:41], v[0:1] op_sel_hi:[1,0]
	v_pk_mul_f32 v[38:39], v[38:39], v[0:1] op_sel_hi:[1,0]
	v_pk_mul_f32 v[36:37], v[36:37], v[0:1] op_sel_hi:[1,0]
	v_pk_mul_f32 v[34:35], v[34:35], v[0:1] op_sel_hi:[1,0]

.LBB0_699:
	s_nop 10
	v_max3_f32 v184, v98, v99, v100
	v_max3_f32 v185, v101, v102, v103
	v_max3_f32 v186, v104, v105, v106
	v_max3_f32 v187, v107, v108, v109
	v_max3_f32 v188, v110, v111, v112
	v_max3_f32 v184, v184, v185, v113
	v_max3_f32 v186, v186, v187, v188
	v_max_f32_e32 v184, v184, v186
	v_mov_b32_e32 v185, v184
	s_nop 1
	v_permlane32_swap_b32_e32 v184, v185
	v_max_f32_e32 v184, v184, v185
	v_add_f32_e32 v185, 0x41800000, v166
	v_cmp_gt_f32_e32 vcc, v184, v185
	s_cbranch_vccz .LBB0_696
	s_nop 0
	v_cndmask_b32_e32 v184, v166, v184, vcc
	v_sub_f32_e32 v166, v166, v184
	v_exp_f32_e32 v166, v166
	s_nop 0
	v_mul_f32_e32 v172, v172, v166
	v_pk_mul_f32 v[80:81], v[80:81], v[166:167] op_sel_hi:[1,0]
	v_pk_mul_f32 v[78:79], v[78:79], v[166:167] op_sel_hi:[1,0]
	v_pk_mul_f32 v[76:77], v[76:77], v[166:167] op_sel_hi:[1,0]
	v_pk_mul_f32 v[74:75], v[74:75], v[166:167] op_sel_hi:[1,0]
	v_pk_mul_f32 v[72:73], v[72:73], v[166:167] op_sel_hi:[1,0]
	v_pk_mul_f32 v[70:71], v[70:71], v[166:167] op_sel_hi:[1,0]
	v_pk_mul_f32 v[68:69], v[68:69], v[166:167] op_sel_hi:[1,0]
	v_pk_mul_f32 v[66:67], v[66:67], v[166:167] op_sel_hi:[1,0]
	v_pk_mul_f32 v[96:97], v[96:97], v[166:167] op_sel_hi:[1,0]
	v_pk_mul_f32 v[94:95], v[94:95], v[166:167] op_sel_hi:[1,0]
	v_pk_mul_f32 v[92:93], v[92:93], v[166:167] op_sel_hi:[1,0]
	v_pk_mul_f32 v[90:91], v[90:91], v[166:167] op_sel_hi:[1,0]
	v_pk_mul_f32 v[88:89], v[88:89], v[166:167] op_sel_hi:[1,0]
	v_pk_mul_f32 v[86:87], v[86:87], v[166:167] op_sel_hi:[1,0]
	v_pk_mul_f32 v[84:85], v[84:85], v[166:167] op_sel_hi:[1,0]
	v_pk_mul_f32 v[82:83], v[82:83], v[166:167] op_sel_hi:[1,0]
	v_mov_b32_e32 v166, v184
	s_branch .LBB0_696

.LBB0_715:
	s_nop 10
	v_max3_f32 v50, v34, v35, v36
	v_max3_f32 v51, v37, v38, v39
	v_max3_f32 v52, v40, v41, v42
	v_max3_f32 v53, v43, v44, v45
	v_max3_f32 v54, v46, v47, v48
	v_max3_f32 v50, v50, v51, v49
	v_max3_f32 v52, v52, v53, v54
	v_max_f32_e32 v50, v50, v52
	v_mov_b32_e32 v51, v50
	s_nop 1
	v_permlane32_swap_b32_e32 v50, v51
	v_max_f32_e32 v50, v50, v51
	v_add_f32_e32 v51, 0x41800000, v168
	v_cmp_gt_f32_e32 vcc, v50, v51
	s_cbranch_vccz .LBB0_717
	s_nop 0
	v_cndmask_b32_e32 v50, v168, v50, vcc
	v_sub_f32_e32 v51, v168, v50
	v_exp_f32_e32 v52, v51
	s_nop 0
	v_mul_f32_e32 v51, v169, v52
	v_pk_mul_f32 v[32:33], v[32:33], v[52:53] op_sel_hi:[1,0]
	v_pk_mul_f32 v[30:31], v[30:31], v[52:53] op_sel_hi:[1,0]
	v_pk_mul_f32 v[28:29], v[28:29], v[52:53] op_sel_hi:[1,0]
	v_pk_mul_f32 v[26:27], v[26:27], v[52:53] op_sel_hi:[1,0]
	v_pk_mul_f32 v[24:25], v[24:25], v[52:53] op_sel_hi:[1,0]
	v_pk_mul_f32 v[22:23], v[22:23], v[52:53] op_sel_hi:[1,0]
	v_pk_mul_f32 v[20:21], v[20:21], v[52:53] op_sel_hi:[1,0]
	v_pk_mul_f32 v[18:19], v[18:19], v[52:53] op_sel_hi:[1,0]
	v_pk_mul_f32 v[16:17], v[16:17], v[52:53] op_sel_hi:[1,0]
	v_pk_mul_f32 v[14:15], v[14:15], v[52:53] op_sel_hi:[1,0]
	v_pk_mul_f32 v[12:13], v[12:13], v[52:53] op_sel_hi:[1,0]
	v_pk_mul_f32 v[10:11], v[10:11], v[52:53] op_sel_hi:[1,0]
	v_pk_mul_f32 v[8:9], v[8:9], v[52:53] op_sel_hi:[1,0]
	v_pk_mul_f32 v[6:7], v[6:7], v[52:53] op_sel_hi:[1,0]
	v_pk_mul_f32 v[4:5], v[4:5], v[52:53] op_sel_hi:[1,0]
	v_pk_mul_f32 v[2:3], v[2:3], v[52:53] op_sel_hi:[1,0]
	v_mov_b64_e32 v[168:169], v[50:51]

.LBB0_724:
	s_nop 10
	v_max3_f32 v0, v66, v67, v68
	v_max3_f32 v2, v69, v70, v71
	v_max3_f32 v3, v72, v73, v74
	v_max3_f32 v4, v75, v76, v77
	v_max3_f32 v5, v78, v79, v80
	v_max3_f32 v0, v0, v2, v81
	v_max3_f32 v3, v3, v4, v5
	v_max_f32_e32 v0, v0, v3
	v_mov_b32_e32 v2, v0
	s_nop 1
	v_permlane32_swap_b32_e32 v0, v2
	v_max_f32_e32 v0, v0, v2
	v_add_f32_e32 v2, 0x41800000, v168
	v_cmp_gt_f32_e32 vcc, v0, v2
	s_cbranch_vccz .LBB0_726
	s_nop 0
	v_cndmask_b32_e32 v0, v168, v0, vcc
	v_sub_f32_e32 v2, v168, v0
	v_exp_f32_e32 v2, v2
	v_mov_b64_e32 v[176:177], v[0:1]
	v_mul_f32_e32 v148, v179, v2
	v_pk_mul_f32 v[32:33], v[64:65], v[2:3] op_sel_hi:[1,0]
	v_pk_mul_f32 v[30:31], v[62:63], v[2:3] op_sel_hi:[1,0]
	v_pk_mul_f32 v[28:29], v[60:61], v[2:3] op_sel_hi:[1,0]
	v_pk_mul_f32 v[26:27], v[58:59], v[2:3] op_sel_hi:[1,0]
	v_pk_mul_f32 v[24:25], v[56:57], v[2:3] op_sel_hi:[1,0]
	v_pk_mul_f32 v[22:23], v[54:55], v[2:3] op_sel_hi:[1,0]
	v_pk_mul_f32 v[20:21], v[52:53], v[2:3] op_sel_hi:[1,0]
	v_pk_mul_f32 v[18:19], v[50:51], v[2:3] op_sel_hi:[1,0]
	v_pk_mul_f32 v[16:17], v[48:49], v[2:3] op_sel_hi:[1,0]
	v_pk_mul_f32 v[14:15], v[46:47], v[2:3] op_sel_hi:[1,0]
	v_pk_mul_f32 v[12:13], v[44:45], v[2:3] op_sel_hi:[1,0]
	v_pk_mul_f32 v[10:11], v[42:43], v[2:3] op_sel_hi:[1,0]
	v_pk_mul_f32 v[8:9], v[40:41], v[2:3] op_sel_hi:[1,0]
	v_pk_mul_f32 v[6:7], v[38:39], v[2:3] op_sel_hi:[1,0]
	v_pk_mul_f32 v[4:5], v[36:37], v[2:3] op_sel_hi:[1,0]
	v_pk_mul_f32 v[2:3], v[34:35], v[2:3] op_sel_hi:[1,0]
	v_mov_b64_e32 v[146:147], v[176:177]
	s_cbranch_execnz .LBB0_707
	s_branch .LBB0_706

.LBB0_764:
	v_add_u32_e32 v0, 1, v184
	v_cmp_lt_i32_e32 vcc, v184, v159
	s_nop 1
	v_cndmask_b32_e32 v182, -1, v0, vcc
	v_cmp_gt_i32_e32 vcc, 0, v182
	s_nop 1
	v_cndmask_b32_e32 v50, v182, v184, vcc
	v_lshlrev_b32_e32 v34, 5, v50
	v_ashrrev_i32_e32 v35, 31, v34
	v_lshl_add_u64 v[52:53], v[174:175], 0, v[34:35]
	v_mad_u64_u32 v[54:55], s[40:41], v52, s80, v[178:179]
	v_mov_b32_e32 v0, v55
	v_mad_u64_u32 v[52:53], s[40:41], v53, s80, v[0:1]
	v_ashrrev_i32_e32 v51, 31, v50
	v_mov_b32_e32 v55, v52
	v_lshlrev_b64 v[50:51], 12, v[50:51]
	v_lshl_add_u64 v[50:51], v[176:177], 0, v[50:51]
	s_add_u32 m0, s98, 0x1000
	v_mad_i64_i32 v[232:233], s[100:101], v224, s99, v[54:55]
	v_add_u32_e32 v232, v228, v232
	global_load_lds_dwordx4 v[232:233], off
	s_add_u32 m0, s98, 0x1400
	v_mad_i64_i32 v[232:233], s[100:101], v225, s99, v[54:55]
	v_add_u32_e32 v232, v229, v232
	global_load_lds_dwordx4 v[232:233], off
	s_add_u32 m0, s98, 0x1800
	v_mad_i64_i32 v[232:233], s[100:101], v226, s99, v[54:55]
	v_add_u32_e32 v232, v228, v232
	global_load_lds_dwordx4 v[232:233], off
	s_add_u32 m0, s98, 0x1c00
	v_mad_i64_i32 v[232:233], s[100:101], v227, s99, v[54:55]
	v_add_u32_e32 v232, v229, v232
	global_load_lds_dwordx4 v[232:233], off
	global_load_dwordx4 v[126:129], v[50:51], off
	global_load_dwordx4 v[122:125], v[50:51], off offset:16
	global_load_dwordx4 v[118:121], v[50:51], off offset:2048
	global_load_dwordx4 v[114:117], v[50:51], off offset:2064
	s_waitcnt vmcnt(12)
	ds_read_b128 v[142:145], v234
	ds_read_b128 v[134:137], v235
	ds_read_b128 v[130:133], v236
	ds_read_b128 v[138:141], v237
	s_waitcnt lgkmcnt(3)
	v_mfma_f32_32x32x16_bf16 v[34:49], v[142:145], v[94:97], 0
	v_cmp_lt_i32_e64 s[40:41], -1, v182
	s_waitcnt lgkmcnt(2)
	v_mfma_f32_32x32x16_bf16 v[34:49], v[134:137], v[86:89], v[34:49]
	s_waitcnt lgkmcnt(1)
	v_mfma_f32_32x32x16_bf16 v[34:49], v[130:133], v[82:85], v[34:49]
	s_waitcnt lgkmcnt(0)
	v_mfma_f32_32x32x16_bf16 v[34:49], v[138:141], v[90:93], v[34:49]
	s_nop 11
	v_max3_f32 v0, v34, v35, v36
	v_max3_f32 v50, v37, v38, v39
	v_max3_f32 v51, v40, v41, v42
	v_max3_f32 v52, v43, v44, v45
	v_max3_f32 v53, v46, v47, v48
	v_max3_f32 v0, v0, v50, v49
	v_max3_f32 v51, v51, v52, v53
	v_max_f32_e32 v0, v0, v51
	v_mov_b32_e32 v50, v0
	s_nop 1
	v_permlane32_swap_b32_e32 v0, v50
	v_max_f32_e32 v0, v0, v50
	v_add_f32_e32 v50, 0x41800000, v183
	v_cmp_gt_f32_e32 vcc, v0, v50
	s_cbranch_vccz .LBB0_766
	s_nop 0
	v_cndmask_b32_e32 v180, v183, v0, vcc
	v_sub_f32_e32 v0, v183, v180
	v_exp_f32_e32 v0, v0
	s_nop 0
	v_mul_f32_e32 v71, v71, v0
	v_pk_mul_f32 v[32:33], v[32:33], v[0:1] op_sel_hi:[1,0]
	v_pk_mul_f32 v[30:31], v[30:31], v[0:1] op_sel_hi:[1,0]
	v_pk_mul_f32 v[28:29], v[28:29], v[0:1] op_sel_hi:[1,0]
	v_pk_mul_f32 v[26:27], v[26:27], v[0:1] op_sel_hi:[1,0]
	v_pk_mul_f32 v[24:25], v[24:25], v[0:1] op_sel_hi:[1,0]
	v_pk_mul_f32 v[22:23], v[22:23], v[0:1] op_sel_hi:[1,0]
	v_pk_mul_f32 v[20:21], v[20:21], v[0:1] op_sel_hi:[1,0]
	v_pk_mul_f32 v[18:19], v[18:19], v[0:1] op_sel_hi:[1,0]
	v_pk_mul_f32 v[16:17], v[16:17], v[0:1] op_sel_hi:[1,0]
	v_pk_mul_f32 v[14:15], v[14:15], v[0:1] op_sel_hi:[1,0]
	v_pk_mul_f32 v[12:13], v[12:13], v[0:1] op_sel_hi:[1,0]
	v_pk_mul_f32 v[10:11], v[10:11], v[0:1] op_sel_hi:[1,0]
	v_pk_mul_f32 v[8:9], v[8:9], v[0:1] op_sel_hi:[1,0]
	v_pk_mul_f32 v[6:7], v[6:7], v[0:1] op_sel_hi:[1,0]
	v_pk_mul_f32 v[4:5], v[4:5], v[0:1] op_sel_hi:[1,0]
	v_pk_mul_f32 v[2:3], v[2:3], v[0:1] op_sel_hi:[1,0]
	s_branch .LBB0_767

.LBB0_767:
	v_pk_add_f32 v[34:35], v[34:35], v[180:181] op_sel_hi:[1,0] neg_lo:[0,1] neg_hi:[0,1]
	v_pk_add_f32 v[36:37], v[36:37], v[180:181] op_sel_hi:[1,0] neg_lo:[0,1] neg_hi:[0,1]
	v_exp_f32_e32 v50, v34
	v_exp_f32_e32 v51, v35
	v_exp_f32_e32 v52, v36
	v_exp_f32_e32 v53, v37
	v_pk_add_f32 v[36:37], v[38:39], v[180:181] op_sel_hi:[1,0] neg_lo:[0,1] neg_hi:[0,1]
	v_pk_add_f32 v[34:35], v[50:51], 0 op_sel_hi:[1,0]
	v_exp_f32_e32 v38, v36
	v_exp_f32_e32 v39, v37
	v_pk_add_f32 v[36:37], v[40:41], v[180:181] op_sel_hi:[1,0] neg_lo:[0,1] neg_hi:[0,1]
	v_pk_add_f32 v[40:41], v[42:43], v[180:181] op_sel_hi:[1,0] neg_lo:[0,1] neg_hi:[0,1]
	v_exp_f32_e32 v36, v36
	v_exp_f32_e32 v37, v37
	v_exp_f32_e32 v40, v40
	v_exp_f32_e32 v41, v41
	v_pk_add_f32 v[42:43], v[44:45], v[180:181] op_sel_hi:[1,0] neg_lo:[0,1] neg_hi:[0,1]
	v_pk_add_f32 v[34:35], v[52:53], v[34:35]
	v_exp_f32_e32 v42, v42
	v_exp_f32_e32 v43, v43
	v_pk_add_f32 v[44:45], v[46:47], v[180:181] op_sel_hi:[1,0] neg_lo:[0,1] neg_hi:[0,1]
	v_pk_add_f32 v[34:35], v[38:39], v[34:35]
	v_exp_f32_e32 v44, v44
	v_exp_f32_e32 v45, v45
	v_pk_add_f32 v[46:47], v[48:49], v[180:181] op_sel_hi:[1,0] neg_lo:[0,1] neg_hi:[0,1]
	v_pk_add_f32 v[34:35], v[36:37], v[34:35]
	v_exp_f32_e32 v46, v46
	v_exp_f32_e32 v47, v47
	v_pk_add_f32 v[34:35], v[40:41], v[34:35]
	v_cvt_pk_bf16_f32 v37, v36, v37
	v_pk_add_f32 v[34:35], v[42:43], v[34:35]
	v_cvt_pk_bf16_f32 v36, v38, v39
	v_pk_add_f32 v[34:35], v[44:45], v[34:35]
	v_cvt_pk_bf16_f32 v73, v46, v47
	v_pk_add_f32 v[34:35], v[46:47], v[34:35]
	v_cvt_pk_bf16_f32 v72, v44, v45
	v_pk_add_f32 v[34:35], v[34:35], v[34:35] op_sel:[0,1] op_sel_hi:[1,0]
	v_cvt_pk_bf16_f32 v70, v40, v41
	v_mov_b32_e32 v0, v34
	s_nop 1
	v_permlane32_swap_b32_e32 v34, v0
	v_add_f32_e32 v0, v34, v0
	v_cvt_pk_bf16_f32 v35, v52, v53
	v_cvt_pk_bf16_f32 v34, v50, v51
	v_add_f32_e32 v169, v71, v0
	v_cvt_pk_bf16_f32 v71, v42, v43
	s_waitcnt vmcnt(11)
	v_mfma_f32_32x32x16_bf16 v[2:17], v[110:113], v[34:37], v[2:17]
	s_mov_b64 s[54:55], -1
	s_or_b64 s[50:51], s[50:51], exec
	s_waitcnt vmcnt(9)
	v_mfma_f32_32x32x16_bf16 v[18:33], v[102:105], v[34:37], v[18:33]
	s_nop 7
	v_mov_b64_e32 v[64:65], v[16:17]
	v_mov_b64_e32 v[62:63], v[14:15]
	v_mov_b64_e32 v[60:61], v[12:13]
	v_mov_b64_e32 v[58:59], v[10:11]
	v_mov_b64_e32 v[56:57], v[8:9]
	v_mov_b64_e32 v[54:55], v[6:7]
	v_mov_b64_e32 v[52:53], v[4:5]
	v_mov_b64_e32 v[48:49], v[32:33]
	v_mov_b64_e32 v[50:51], v[2:3]
	v_mov_b64_e32 v[46:47], v[30:31]
	v_mov_b64_e32 v[44:45], v[28:29]
	v_mov_b64_e32 v[42:43], v[26:27]
	v_mov_b64_e32 v[40:41], v[24:25]
	v_mov_b64_e32 v[38:39], v[22:23]
	v_mov_b64_e32 v[36:37], v[20:21]
	v_mov_b64_e32 v[34:35], v[18:19]
	v_mfma_f32_32x32x16_bf16 v[50:65], v[106:109], v[70:73], v[50:65]
	s_waitcnt vmcnt(8)
	v_mfma_f32_32x32x16_bf16 v[34:49], v[98:101], v[70:73], v[34:49]
	s_and_saveexec_b64 s[52:53], s[40:41]
	s_cbranch_execz .LBB0_763
	v_add_u32_e32 v184, 1, v182
	v_cmp_lt_u32_e32 vcc, v182, v159
	v_mov_b32_e32 v3, v1
	s_waitcnt vmcnt(4)
	ds_read_b128 v[66:69], v234 offset:4096
	ds_read_b128 v[154:157], v235 offset:4096
	ds_read_b128 v[150:153], v236 offset:4096
	ds_read_b128 v[146:149], v237 offset:4096
	s_waitcnt lgkmcnt(3)
	v_mfma_f32_32x32x16_bf16 v[66:81], v[66:69], v[94:97], 0
	v_cndmask_b32_e32 v2, v182, v184, vcc
	v_lshlrev_b32_e32 v0, 5, v2
	v_lshl_add_u64 v[4:5], v[174:175], 0, v[0:1]
	v_mad_u64_u32 v[6:7], s[40:41], v4, s80, v[178:179]
	v_mov_b32_e32 v0, v7
	v_mad_u64_u32 v[4:5], s[40:41], v5, s80, v[0:1]
	v_mov_b32_e32 v7, v4
	v_lshlrev_b64 v[2:3], 12, v[2:3]
	v_lshl_add_u64 v[2:3], v[176:177], 0, v[2:3]
	s_add_u32 m0, s98, 0x0
	v_mad_i64_i32 v[232:233], s[100:101], v224, s99, v[6:7]
	v_add_u32_e32 v232, v228, v232
	global_load_lds_dwordx4 v[232:233], off
	s_add_u32 m0, s98, 0x400
	v_mad_i64_i32 v[232:233], s[100:101], v225, s99, v[6:7]
	v_add_u32_e32 v232, v229, v232
	global_load_lds_dwordx4 v[232:233], off
	s_add_u32 m0, s98, 0x800
	v_mad_i64_i32 v[232:233], s[100:101], v226, s99, v[6:7]
	v_add_u32_e32 v232, v228, v232
	global_load_lds_dwordx4 v[232:233], off
	s_add_u32 m0, s98, 0xc00
	v_mad_i64_i32 v[232:233], s[100:101], v227, s99, v[6:7]
	v_add_u32_e32 v232, v229, v232
	global_load_lds_dwordx4 v[232:233], off
	global_load_dwordx4 v[110:113], v[2:3], off
	global_load_dwordx4 v[106:109], v[2:3], off offset:16
	global_load_dwordx4 v[102:105], v[2:3], off offset:2048
	global_load_dwordx4 v[98:101], v[2:3], off offset:2064
	s_waitcnt lgkmcnt(2)
	v_mfma_f32_32x32x16_bf16 v[66:81], v[154:157], v[86:89], v[66:81]
	v_cmp_ge_u32_e64 s[40:41], v182, v159
	s_waitcnt lgkmcnt(1)
	v_mfma_f32_32x32x16_bf16 v[66:81], v[150:153], v[82:85], v[66:81]
	s_waitcnt lgkmcnt(0)
	v_mfma_f32_32x32x16_bf16 v[66:81], v[146:149], v[90:93], v[66:81]
	s_nop 11
	v_max3_f32 v0, v66, v67, v68
	v_max3_f32 v2, v69, v70, v71
	v_max3_f32 v3, v72, v73, v74
	v_max3_f32 v4, v75, v76, v77
	v_max3_f32 v5, v78, v79, v80
	v_max3_f32 v0, v0, v2, v81
	v_max3_f32 v3, v3, v4, v5
	v_max_f32_e32 v0, v0, v3
	v_mov_b32_e32 v2, v0
	s_nop 1
	v_permlane32_swap_b32_e32 v0, v2
	v_max_f32_e32 v0, v0, v2
	v_add_f32_e32 v2, 0x41800000, v180
	v_cmp_gt_f32_e32 vcc, v0, v2
	s_cbranch_vccnz .LBB0_761
	v_mov_b64_e32 v[182:183], v[180:181]
	v_mov_b32_e32 v0, v169
	v_mov_b32_e32 v183, v180
	v_mov_b32_e32 v2, v50
	v_mov_b32_e32 v3, v51
	v_mov_b32_e32 v4, v52
	v_mov_b32_e32 v5, v53
	v_mov_b32_e32 v6, v54
	v_mov_b32_e32 v7, v55
	v_mov_b32_e32 v8, v56
	v_mov_b32_e32 v9, v57
	v_mov_b32_e32 v10, v58
	v_mov_b32_e32 v11, v59
	v_mov_b32_e32 v12, v60
	v_mov_b32_e32 v13, v61
	v_mov_b32_e32 v14, v62
	v_mov_b32_e32 v15, v63
	v_mov_b32_e32 v16, v64
	v_mov_b32_e32 v17, v65
	v_mov_b32_e32 v18, v34
	v_mov_b32_e32 v19, v35
	v_mov_b32_e32 v20, v36
	v_mov_b32_e32 v21, v37
	v_mov_b32_e32 v22, v38
	v_mov_b32_e32 v23, v39
	v_mov_b32_e32 v24, v40
	v_mov_b32_e32 v25, v41
	v_mov_b32_e32 v26, v42
	v_mov_b32_e32 v27, v43
	v_mov_b32_e32 v28, v44
	v_mov_b32_e32 v29, v45
	v_mov_b32_e32 v30, v46
	v_mov_b32_e32 v31, v47
	v_mov_b32_e32 v32, v48
	v_mov_b32_e32 v33, v49
	s_branch .LBB0_762

.LBB0_856:
	s_nop 10
	v_max3_f32 v50, v34, v35, v36
	v_max3_f32 v51, v37, v38, v39
	v_max3_f32 v52, v40, v41, v42
	v_max3_f32 v53, v43, v44, v45
	v_max3_f32 v54, v46, v47, v48
	v_max3_f32 v50, v50, v51, v49
	v_max3_f32 v52, v52, v53, v54
	v_max_f32_e32 v50, v50, v52
	v_mov_b32_e32 v51, v50
	s_nop 1
	v_permlane32_swap_b32_e32 v50, v51
	v_max_f32_e32 v50, v50, v51
	v_add_f32_e32 v51, 0x41800000, v164
	v_cmp_gt_f32_e32 vcc, v50, v51
	s_cbranch_vccz .LBB0_858
	s_nop 0
	v_cndmask_b32_e32 v51, v164, v50, vcc
	v_sub_f32_e32 v50, v164, v51
	v_exp_f32_e32 v50, v50
	v_mov_b32_e32 v164, v51
	v_mul_f32_e32 v70, v70, v50
	v_pk_mul_f32 v[16:17], v[16:17], v[50:51] op_sel_hi:[1,0]
	v_pk_mul_f32 v[14:15], v[14:15], v[50:51] op_sel_hi:[1,0]
	v_pk_mul_f32 v[12:13], v[12:13], v[50:51] op_sel_hi:[1,0]
	v_pk_mul_f32 v[10:11], v[10:11], v[50:51] op_sel_hi:[1,0]
	v_pk_mul_f32 v[8:9], v[8:9], v[50:51] op_sel_hi:[1,0]
	v_pk_mul_f32 v[6:7], v[6:7], v[50:51] op_sel_hi:[1,0]
	v_pk_mul_f32 v[4:5], v[4:5], v[50:51] op_sel_hi:[1,0]
	v_pk_mul_f32 v[2:3], v[2:3], v[50:51] op_sel_hi:[1,0]
	v_pk_mul_f32 v[32:33], v[32:33], v[50:51] op_sel_hi:[1,0]
	v_pk_mul_f32 v[30:31], v[30:31], v[50:51] op_sel_hi:[1,0]
	v_pk_mul_f32 v[28:29], v[28:29], v[50:51] op_sel_hi:[1,0]
	v_pk_mul_f32 v[26:27], v[26:27], v[50:51] op_sel_hi:[1,0]
	v_pk_mul_f32 v[24:25], v[24:25], v[50:51] op_sel_hi:[1,0]
	v_pk_mul_f32 v[22:23], v[22:23], v[50:51] op_sel_hi:[1,0]
	v_pk_mul_f32 v[20:21], v[20:21], v[50:51] op_sel_hi:[1,0]
	v_pk_mul_f32 v[18:19], v[18:19], v[50:51] op_sel_hi:[1,0]

.LBB0_861:
	s_nop 10
	v_max3_f32 v2, v66, v67, v68
	v_max3_f32 v3, v69, v70, v71
	v_max3_f32 v4, v72, v73, v74
	v_max3_f32 v5, v75, v76, v77
	v_max3_f32 v6, v78, v79, v80
	v_max3_f32 v2, v2, v3, v81
	v_max3_f32 v4, v4, v5, v6
	v_max_f32_e32 v2, v2, v4
	v_mov_b32_e32 v3, v2
	s_nop 1
	v_permlane32_swap_b32_e32 v2, v3
	v_max_f32_e32 v2, v2, v3
	v_add_f32_e32 v3, 0x41800000, v164
	v_cmp_gt_f32_e32 vcc, v2, v3
	s_cbranch_vccnz .LBB0_851
	v_mov_b64_e32 v[146:147], v[164:165]
	v_mov_b32_e32 v148, v189
	v_mov_b32_e32 v18, v34
	v_mov_b32_e32 v19, v35
	v_mov_b32_e32 v20, v36
	v_mov_b32_e32 v21, v37
	v_mov_b32_e32 v22, v38
	v_mov_b32_e32 v23, v39
	v_mov_b32_e32 v24, v40
	v_mov_b32_e32 v25, v41
	v_mov_b32_e32 v26, v42
	v_mov_b32_e32 v27, v43
	v_mov_b32_e32 v28, v44
	v_mov_b32_e32 v29, v45
	v_mov_b32_e32 v30, v46
	v_mov_b32_e32 v31, v47
	v_mov_b32_e32 v32, v48
	v_mov_b32_e32 v33, v49
	v_mov_b32_e32 v2, v50
	v_mov_b32_e32 v3, v51
	v_mov_b32_e32 v4, v52
	v_mov_b32_e32 v5, v53
	v_mov_b32_e32 v6, v54
	v_mov_b32_e32 v7, v55
	v_mov_b32_e32 v8, v56
	v_mov_b32_e32 v9, v57
	v_mov_b32_e32 v10, v58
	v_mov_b32_e32 v11, v59
	v_mov_b32_e32 v12, v60
	v_mov_b32_e32 v13, v61
	v_mov_b32_e32 v14, v62
	v_mov_b32_e32 v15, v63
	v_mov_b32_e32 v16, v64
	v_mov_b32_e32 v17, v65
	s_branch .LBB0_852
